# adds early issue of the attention K/V tile loads into dedicated staging registers
# speedup vs baseline: 1.0085x; 1.0033x over previous
; __device__ __forceinline__ float fadd_s(float a, float b) { float r; asm("v_add_f32 %0, %1, %2" : "=v"(r) : "v"(a), "v"(b)); return r; }
; #define SWAIT() asm volatile("s_waitcnt vmcnt(0)" ::: "memory")
; __device__ __forceinline__ void finishSM(f32x16& p0, f32x16& p1, float& l_reg, bf16x8& pa0, bf16x8& pa1, bf16x8& pa2, bf16x8& pa3) {
; #pragma unroll
;   for (int r = 0; r < 16; ++r) p1[r] = __builtin_amdgcn_exp2f(p1[r]);
;   asm volatile("s_nop 0" : "+v"(p1));
;   float s0 = fadd_s(p0[0], p0[1]), s1 = fadd_s(p0[2], p0[3]), s2 = fadd_s(p0[4], p0[5]), s3 = fadd_s(p0[6], p0[7]);
; #pragma unroll
;   for (int r = 8; r < 16; r += 4) { s0 = fadd_s(s0, p0[r]); s1 = fadd_s(s1, p0[r + 1]); s2 = fadd_s(s2, p0[r + 2]); s3 = fadd_s(s3, p0[r + 3]); }
; #pragma unroll
;   for (int r = 0; r < 16; r += 4) { s0 = fadd_s(s0, p1[r]); s1 = fadd_s(s1, p1[r + 1]); s2 = fadd_s(s2, p1[r + 2]); s3 = fadd_s(s3, p1[r + 3]); }
;   l_reg = fadd_s(l_reg, fadd_s(fadd_s(s0, s1), fadd_s(s2, s3)));
;     ...
;   PK4(p0, 0, pa0); PK4(p0, 8, pa1); PK4(p1, 0, pa2); PK4(p1, 8, pa3);
;     ...
; }
; __device__ __forceinline__ void qkt(f32x16& p0, f32x16& p1, const bf16_t* Ks, const bf16x8* qr, int r32, int hi) {
;   p0 = f32x16{}; p1 = f32x16{};
; #pragma unroll
;   for (int d0 = 0; d0 < 8; ++d0) { int cb = (d0 * 16 + hi * 8) * 2;
;     bf16x8 b0 = *reinterpret_cast<const bf16x8*>((const char*)Ks + KSWZ(r32, cb));
;     bf16x8 b1 = *reinterpret_cast<const bf16x8*>((const char*)Ks + KSWZ(32 + r32, cb));
;     p0 = __builtin_amdgcn_mfma_f32_32x32x16_bf16(b0, qr[d0], p0, 0, 0, 0);
;     p1 = __builtin_amdgcn_mfma_f32_32x32x16_bf16(b1, qr[d0], p1, 0, 0, 0); }
; }
; __device__ __forceinline__ void attn_dense_body(const bf16_t* Qb, const bf16_t* __restrict__ Kh, const bf16_t* __restrict__ Vh, bf16_t* Ob, int seq, char* lds, const int wid,
;                                                 const float* __restrict__ qg, const float* __restrict__ rope, int t0) {
;     ...
;   f32x16 pA0, pA1, pB0, pB1; bf16x8 pa0, pa1, pa2, pa3; const int NT = seq / KVBLK;
;   if (wid >= 4) __builtin_amdgcn_s_setprio(1);
;   SLOAD(0, 0); SWAIT(); SWRITE(0, 0);
;   SLOAD(0, KVBLK); SWAIT(); SWRITE((int)SHM_V, 0); __syncthreads();
;   qkt(pA0, pA1, K_lds, qr, r32, hi); expHalf(pA0);
;   int o0 = 0, o1 = (int)SHM_V, o2 = 2 * (int)SHM_V;
.LBB0_495:
	s_mov_b32 s12, s13
	s_mov_b32 s101, 0xffdf0000
	v_add_co_u32_e32 v248, vcc, s101, v152
	s_mov_b32 s101, 0xffea0000
	s_nop 0
	v_addc_co_u32_e32 v249, vcc, -1, v153, vcc
	v_add_co_u32_e32 v250, vcc, s101, v152
	s_nop 1
	v_addc_co_u32_e32 v251, vcc, -1, v153, vcc
	global_load_dwordx4 v[226:229], v[248:249], off
	global_load_dwordx4 v[230:233], v[248:249], off offset:-1024
	global_load_dwordx4 v[234:237], v[250:251], off
	global_load_dwordx4 v[238:241], v[250:251], off offset:-1024
	s_add_i32 s13, s11, 0
	v_add_u32_e32 v84, s13, v177
	ds_read_b128 v[80:83], v84 offset:49152
	ds_read_b128 v[84:87], v84 offset:57344
	v_add_u32_e32 v191, s13, v178
	ds_read_b128 v[210:213], v191 offset:49152
	ds_read_b128 v[214:217], v191 offset:57344
	v_add_u32_e32 v191, s13, v173
	s_waitcnt lgkmcnt(3)
	v_mfma_f32_32x32x16_bf16 v[96:111], v[80:83], v[140:143], 0
	v_exp_f32_e32 v64, v64
	v_exp_f32_e32 v65, v65
	v_exp_f32_e32 v66, v66
	v_exp_f32_e32 v67, v67
	v_exp_f32_e32 v68, v68
	v_exp_f32_e32 v69, v69
	v_exp_f32_e32 v70, v70
	s_waitcnt lgkmcnt(2)
	v_mfma_f32_32x32x16_bf16 v[80:95], v[84:87], v[140:143], 0
	v_exp_f32_e32 v71, v71
	v_exp_f32_e32 v72, v72
	v_exp_f32_e32 v73, v73
	v_exp_f32_e32 v74, v74
	v_exp_f32_e32 v75, v75
	v_exp_f32_e32 v76, v76
	v_exp_f32_e32 v77, v77
	s_waitcnt lgkmcnt(1)
	v_mfma_f32_32x32x16_bf16 v[96:111], v[210:213], v[136:139], v[96:111]
	v_exp_f32_e32 v78, v78
	v_exp_f32_e32 v79, v79
	v_add_f32 v192, v147, v188
	v_add_f32 v195, v146, v187
	v_add_f32 v204, v189, v190
	s_nop 0
	v_add_f32 v192, v192, v149
	s_waitcnt lgkmcnt(0)
	v_mfma_f32_32x32x16_bf16 v[80:95], v[214:217], v[136:139], v[80:95]
	ds_read_b128 v[210:213], v191 offset:49152
	ds_read_b128 v[214:217], v191 offset:57344
	v_add_u32_e32 v191, s13, v169
	v_add_f32 v195, v195, v150
	v_add_f32 v204, v204, v151
	v_add_f32 v192, v192, v184
	s_nop 0
	v_add_f32 v195, v195, v185
	s_waitcnt lgkmcnt(1)
	v_mfma_f32_32x32x16_bf16 v[96:111], v[210:213], v[132:135], v[96:111]
	v_add_f32 v204, v204, v186
	s_waitcnt lgkmcnt(0)
	v_mfma_f32_32x32x16_bf16 v[80:95], v[214:217], v[132:135], v[80:95]
	ds_read_b128 v[210:213], v191 offset:49152
	ds_read_b128 v[214:217], v191 offset:57344
	v_add_u32_e32 v191, s13, v167
	s_waitcnt lgkmcnt(1)
	v_mfma_f32_32x32x16_bf16 v[96:111], v[210:213], v[128:131], v[96:111]
	s_waitcnt lgkmcnt(0)
	v_mfma_f32_32x32x16_bf16 v[80:95], v[214:217], v[128:131], v[80:95]
	ds_read_b128 v[210:213], v191 offset:49152
	ds_read_b128 v[214:217], v191 offset:57344
	v_add_u32_e32 v191, s13, v163
	s_waitcnt lgkmcnt(1)
	v_mfma_f32_32x32x16_bf16 v[96:111], v[210:213], v[124:127], v[96:111]
	s_waitcnt lgkmcnt(0)
	v_mfma_f32_32x32x16_bf16 v[80:95], v[214:217], v[124:127], v[80:95]
	ds_read_b128 v[210:213], v191 offset:49152
	ds_read_b128 v[214:217], v191 offset:57344
	v_add_u32_e32 v191, s13, v162
	s_waitcnt lgkmcnt(1)
	v_mfma_f32_32x32x16_bf16 v[96:111], v[210:213], v[120:123], v[96:111]
	s_waitcnt lgkmcnt(0)
	v_mfma_f32_32x32x16_bf16 v[80:95], v[214:217], v[120:123], v[80:95]
	ds_read_b128 v[210:213], v191 offset:49152
	ds_read_b128 v[214:217], v191 offset:57344
	v_add_u32_e32 v191, s13, v159
	s_waitcnt lgkmcnt(1)
	v_mfma_f32_32x32x16_bf16 v[96:111], v[210:213], v[116:119], v[96:111]
	s_waitcnt lgkmcnt(0)
	v_mfma_f32_32x32x16_bf16 v[80:95], v[214:217], v[116:119], v[80:95]
	ds_read_b128 v[210:213], v191 offset:49152
	ds_read_b128 v[214:217], v191 offset:57344
	v_add_f32 v191, v144, v145
	s_nop 0
	v_cvt_pk_bf16_f32 v144, v144, v145
	v_cvt_pk_bf16_f32 v145, v147, v188
	v_cvt_pk_bf16_f32 v146, v146, v187
	v_cvt_pk_bf16_f32 v147, v189, v190
	s_nop 0
	v_add_f32 v191, v191, v148
	v_add_f32 v192, v192, v65
	v_add_f32 v195, v195, v66
	v_add_f32 v204, v204, v67
	s_waitcnt lgkmcnt(1)
	v_mfma_f32_32x32x16_bf16 v[96:111], v[210:213], v[112:115], v[96:111]
	v_add_f32 v191, v191, v183
	s_nop 1
	v_cvt_pk_bf16_f32 v148, v148, v149
	v_cvt_pk_bf16_f32 v149, v150, v151
	v_cvt_pk_bf16_f32 v150, v183, v184
	v_cvt_pk_bf16_f32 v151, v185, v186
	s_nop 0
	v_add_f32 v191, v191, v64
	v_add_f32 v192, v192, v69
	v_add_f32 v195, v195, v70
	v_add_f32 v204, v204, v71
	v_permlane32_swap_b32_e32 v144, v146
	v_add_f32 v191, v191, v68
	s_nop 1
	v_cvt_pk_bf16_f32 v64, v64, v65
	v_cvt_pk_bf16_f32 v65, v66, v67
	v_cvt_pk_bf16_f32 v66, v68, v69
	v_cvt_pk_bf16_f32 v67, v70, v71
	s_nop 0
	v_add_f32 v191, v191, v72
	v_add_f32 v192, v192, v73
	v_add_f32 v195, v195, v74
	v_add_f32 v204, v204, v75
	v_permlane32_swap_b32_e32 v145, v147
	s_nop 1
	v_cvt_pk_bf16_f32 v68, v72, v73
	v_cvt_pk_bf16_f32 v69, v74, v75
	v_cvt_pk_bf16_f32 v70, v76, v77
	v_cvt_pk_bf16_f32 v71, v78, v79
	v_add_f32 v191, v191, v76
	v_add_f32 v192, v192, v77
	v_permlane32_swap_b32_e32 v148, v150
	s_nop 1
	v_add_f32 v191, v191, v192
	v_permlane32_swap_b32_e32 v149, v151
	v_permlane32_swap_b32_e32 v64, v66
	v_permlane32_swap_b32_e32 v65, v67
	v_permlane32_swap_b32_e32 v68, v70
	v_permlane32_swap_b32_e32 v69, v71
	s_waitcnt lgkmcnt(0)
	v_mfma_f32_32x32x16_bf16 v[80:95], v[214:217], v[112:115], v[80:95]
	v_add_f32 v195, v195, v78
	v_add_f32 v204, v204, v79
	s_nop 0
	v_add_f32 v192, v195, v204
	s_nop 0
	v_add_f32 v191, v191, v192
	s_nop 0
	v_add_f32 v179, v179, v191
	v_add_u32_e32 v183, s9, v157
	ds_read_b64_tr_b16 v[210:211], v183 offset:0
	ds_read_b64_tr_b16 v[212:213], v183 offset:0x800
	ds_read_b64_tr_b16 v[214:215], v183 offset:0x1000
	ds_read_b64_tr_b16 v[216:217], v183 offset:0x1800
	ds_read_b64_tr_b16 v[218:219], v183 offset:0x2000
	ds_read_b64_tr_b16 v[220:221], v183 offset:0x2800
	ds_read_b64_tr_b16 v[222:223], v183 offset:0x3000
	ds_read_b64_tr_b16 v[224:225], v183 offset:0x3800
	s_waitcnt lgkmcnt(0)
; #define SBAR() __builtin_amdgcn_sched_barrier(0)
; #define SLOAD(i, k0) do { sr_[i].vs0 = ld8(&Vh[(long)((k0) + sr) * LD + sc]); sr_[i].vs1 = ld8(&Vh[(long)((k0) + 32 + sr) * LD + sc]); \
;     sr_[i].ks0 = ld8(&Kh[(long)((k0) + sr) * LD + sc]); sr_[i].ks1 = ld8(&Kh[(long)((k0) + 32 + sr) * LD + sc]); } while (0)
; #define SWAIT() asm volatile("s_waitcnt vmcnt(0)" ::: "memory")
; template <int D0> __device__ __forceinline__ void pv_one(f32x16& od, int vb, bf16x8 pa0, bf16x8 pa1, bf16x8 pa2, bf16x8 pa3) {
;   const s16x4 l0 = tr_read<v_rd_off(D0, 0, 0)>(vb), h0 = tr_read<v_rd_off(D0, 0, 1)>(vb), l1 = tr_read<v_rd_off(D0, 1, 0)>(vb), h1 = tr_read<v_rd_off(D0, 1, 1)>(vb);
;   const s16x4 l2 = tr_read<v_rd_off(D0, 2, 0)>(vb), h2 = tr_read<v_rd_off(D0, 2, 1)>(vb), l3 = tr_read<v_rd_off(D0, 3, 0)>(vb), h3 = tr_read<v_rd_off(D0, 3, 1)>(vb);
;   asm volatile("s_waitcnt lgkmcnt(0)" ::: "memory"); SBAR();
;     ...
;   od = __builtin_amdgcn_mfma_f32_32x32x16_bf16(pa0, PK(l0, h0), od, 0, 0, 0);
;   od = __builtin_amdgcn_mfma_f32_32x32x16_bf16(pa1, PK(l1, h1), od, 0, 0, 0);
;   od = __builtin_amdgcn_mfma_f32_32x32x16_bf16(pa2, PK(l2, h2), od, 0, 0, 0);
;   od = __builtin_amdgcn_mfma_f32_32x32x16_bf16(pa3, PK(l3, h3), od, 0, 0, 0);
;     ...
; }
; __device__ __forceinline__ void pv_d0(f32x16* o, int vb, bf16x8 pa0, bf16x8 pa1, bf16x8 pa2, bf16x8 pa3) {
;   pv_one<0>(o[0], vb, pa0, pa1, pa2, pa3); pv_one<1>(o[1], vb, pa0, pa1, pa2, pa3); pv_one<2>(o[2], vb, pa0, pa1, pa2, pa3); pv_one<3>(o[3], vb, pa0, pa1, pa2, pa3);
; __device__ __forceinline__ void attn_dense_body(const bf16_t* Qb, const bf16_t* __restrict__ Kh, const bf16_t* __restrict__ Vh, bf16_t* Ob, int seq, char* lds, const int wid,
;                                                 const float* __restrict__ qg, const float* __restrict__ rope, int t0) {
;     ...
;   f32x16 pA0, pA1, pB0, pB1; bf16x8 pa0, pa1, pa2, pa3; const int NT = seq / KVBLK;
;   if (wid >= 4) __builtin_amdgcn_s_setprio(1);
;   SLOAD(0, 0); SWAIT(); SWRITE(0, 0);
;   SLOAD(0, KVBLK); SWAIT(); SWRITE((int)SHM_V, 0); __syncthreads();
;   qkt(pA0, pA1, K_lds, qr, r32, hi); expHalf(pA0);
;   int o0 = 0, o1 = (int)SHM_V, o2 = 2 * (int)SHM_V;
	s_nop 0
	v_mfma_f32_32x32x16_bf16 v[0:15], v[144:147], v[210:213], v[0:15]
	ds_read_b64_tr_b16 v[210:211], v183 offset:0x200
	ds_read_b64_tr_b16 v[212:213], v183 offset:0xa00
	v_mfma_f32_32x32x16_bf16 v[0:15], v[148:151], v[214:217], v[0:15]
	ds_read_b64_tr_b16 v[214:215], v183 offset:0x1200
	ds_read_b64_tr_b16 v[216:217], v183 offset:0x1a00
	v_mfma_f32_32x32x16_bf16 v[0:15], v[64:67], v[218:221], v[0:15]
	ds_read_b64_tr_b16 v[218:219], v183 offset:0x2200
	ds_read_b64_tr_b16 v[220:221], v183 offset:0x2a00
	v_mfma_f32_32x32x16_bf16 v[0:15], v[68:71], v[222:225], v[0:15]
	ds_read_b64_tr_b16 v[222:223], v183 offset:0x3200
	ds_read_b64_tr_b16 v[224:225], v183 offset:0x3a00
	s_waitcnt lgkmcnt(0)
	v_mfma_f32_32x32x16_bf16 v[16:31], v[144:147], v[210:213], v[16:31]
	ds_read_b64_tr_b16 v[210:211], v183 offset:0x400
	ds_read_b64_tr_b16 v[212:213], v183 offset:0xc00
	v_mfma_f32_32x32x16_bf16 v[16:31], v[148:151], v[214:217], v[16:31]
	ds_read_b64_tr_b16 v[214:215], v183 offset:0x1400
	ds_read_b64_tr_b16 v[216:217], v183 offset:0x1c00
	v_mfma_f32_32x32x16_bf16 v[16:31], v[64:67], v[218:221], v[16:31]
	ds_read_b64_tr_b16 v[218:219], v183 offset:0x2400
	ds_read_b64_tr_b16 v[220:221], v183 offset:0x2c00
	v_mfma_f32_32x32x16_bf16 v[16:31], v[68:71], v[222:225], v[16:31]
	ds_read_b64_tr_b16 v[222:223], v183 offset:0x3400
	ds_read_b64_tr_b16 v[224:225], v183 offset:0x3c00
	s_waitcnt lgkmcnt(0)
	v_mfma_f32_32x32x16_bf16 v[32:47], v[144:147], v[210:213], v[32:47]
	ds_read_b64_tr_b16 v[210:211], v183 offset:0x600
	ds_read_b64_tr_b16 v[212:213], v183 offset:0xe00
	v_mfma_f32_32x32x16_bf16 v[32:47], v[148:151], v[214:217], v[32:47]
	ds_read_b64_tr_b16 v[214:215], v183 offset:0x1600
	ds_read_b64_tr_b16 v[216:217], v183 offset:0x1e00
	v_mfma_f32_32x32x16_bf16 v[32:47], v[64:67], v[218:221], v[32:47]
	ds_read_b64_tr_b16 v[218:219], v183 offset:0x2600
	ds_read_b64_tr_b16 v[220:221], v183 offset:0x2e00
	v_mfma_f32_32x32x16_bf16 v[32:47], v[68:71], v[222:225], v[32:47]
	ds_read_b64_tr_b16 v[222:223], v183 offset:0x3600
	ds_read_b64_tr_b16 v[224:225], v183 offset:0x3e00
	s_waitcnt lgkmcnt(0)
	v_mfma_f32_32x32x16_bf16 v[48:63], v[144:147], v[210:213], v[48:63]
	s_add_i32 s13, s12, 0
	v_exp_f32_e32 v183, v96
	s_waitcnt vmcnt(0)
	v_exp_f32_e32 v192, v97
	v_exp_f32_e32 v195, v98
	v_exp_f32_e32 v204, v99
	v_exp_f32_e32 v205, v100
	v_mfma_f32_32x32x16_bf16 v[48:63], v[148:151], v[214:217], v[48:63]
	v_exp_f32_e32 v210, v101
	v_exp_f32_e32 v211, v102
	v_exp_f32_e32 v212, v103
	v_exp_f32_e32 v213, v104
	v_exp_f32_e32 v214, v105
	v_exp_f32_e32 v215, v106
	v_exp_f32_e32 v216, v107
	v_mfma_f32_32x32x16_bf16 v[48:63], v[64:67], v[218:221], v[48:63]
	v_add_u32_e32 v64, s13, v170
	s_waitcnt vmcnt(3)
	ds_write_b128 v64, v[226:229]
	v_add_u32_e32 v64, s13, v171
	s_waitcnt vmcnt(1)
	ds_write_b128 v64, v[234:237]
	v_add_u32_e32 v64, s13, v165
	ds_write_b128 v64, v[230:233] offset:49152
	v_add_u32_e32 v64, s13, v168
	v_mfma_f32_32x32x16_bf16 v[48:63], v[68:71], v[222:225], v[48:63]
	v_exp_f32_e32 v217, v108
	v_exp_f32_e32 v218, v109
	v_exp_f32_e32 v219, v110
	v_exp_f32_e32 v220, v111
	s_waitcnt vmcnt(0)
	ds_write_b128 v64, v[238:241] offset:49152
	s_waitcnt lgkmcnt(0)
	s_barrier
	s_mov_b32 s101, 0xfff50000
	v_add_co_u32_e32 v248, vcc, s101, v152
	s_nop 1
	v_addc_co_u32_e32 v249, vcc, -1, v153, vcc
	global_load_dwordx4 v[226:229], v[248:249], off
	global_load_dwordx4 v[230:233], v[248:249], off offset:-1024
	global_load_dwordx4 v[234:237], v[152:153], off
	global_load_dwordx4 v[238:241], v[152:153], off offset:-1024
	v_add_u32_e32 v68, s13, v177
	ds_read_b128 v[64:67], v68 offset:49152
	ds_read_b128 v[68:71], v68 offset:57344
	v_add_u32_e32 v148, s13, v178
	ds_read_b128 v[144:147], v148 offset:49152
	ds_read_b128 v[148:151], v148 offset:57344
	v_exp_f32_e32 v80, v80
	s_waitcnt lgkmcnt(3)
	v_mfma_f32_32x32x16_bf16 v[96:111], v[64:67], v[140:143], 0
	v_exp_f32_e32 v81, v81
	v_exp_f32_e32 v82, v82
	v_exp_f32_e32 v83, v83
	v_exp_f32_e32 v84, v84
	v_exp_f32_e32 v85, v85
	v_exp_f32_e32 v86, v86
	v_exp_f32_e32 v87, v87
	s_waitcnt lgkmcnt(2)
	v_mfma_f32_32x32x16_bf16 v[64:79], v[68:71], v[140:143], 0
	v_exp_f32_e32 v88, v88
	v_exp_f32_e32 v89, v89
	v_exp_f32_e32 v90, v90
	v_exp_f32_e32 v91, v91
	v_exp_f32_e32 v92, v92
	v_exp_f32_e32 v93, v93
	v_exp_f32_e32 v94, v94
	s_waitcnt lgkmcnt(1)
	v_mfma_f32_32x32x16_bf16 v[96:111], v[144:147], v[136:139], v[96:111]
	v_exp_f32_e32 v95, v95
	s_waitcnt lgkmcnt(0)
	v_mfma_f32_32x32x16_bf16 v[64:79], v[148:151], v[136:139], v[64:79]
	v_add_u32_e32 v148, s13, v173
	ds_read_b128 v[144:147], v148 offset:49152
	ds_read_b128 v[148:151], v148 offset:57344
	s_waitcnt lgkmcnt(1)
	v_mfma_f32_32x32x16_bf16 v[96:111], v[144:147], v[132:135], v[96:111]
	s_waitcnt lgkmcnt(0)
	v_mfma_f32_32x32x16_bf16 v[64:79], v[148:151], v[132:135], v[64:79]
	v_add_u32_e32 v148, s13, v169
	ds_read_b128 v[144:147], v148 offset:49152
	ds_read_b128 v[148:151], v148 offset:57344
	s_waitcnt lgkmcnt(1)
	v_mfma_f32_32x32x16_bf16 v[96:111], v[144:147], v[128:131], v[96:111]
	s_waitcnt lgkmcnt(0)
	v_mfma_f32_32x32x16_bf16 v[64:79], v[148:151], v[128:131], v[64:79]
	v_add_u32_e32 v148, s13, v167
	ds_read_b128 v[144:147], v148 offset:49152
	ds_read_b128 v[148:151], v148 offset:57344
	s_waitcnt lgkmcnt(1)
	v_mfma_f32_32x32x16_bf16 v[96:111], v[144:147], v[124:127], v[96:111]
	s_waitcnt lgkmcnt(0)
	v_mfma_f32_32x32x16_bf16 v[64:79], v[148:151], v[124:127], v[64:79]
	v_add_u32_e32 v148, s13, v163
	ds_read_b128 v[144:147], v148 offset:49152
	ds_read_b128 v[148:151], v148 offset:57344
	s_waitcnt lgkmcnt(1)
	v_mfma_f32_32x32x16_bf16 v[96:111], v[144:147], v[120:123], v[96:111]
	s_waitcnt lgkmcnt(0)
; __device__ __forceinline__ void finishSM(f32x16& p0, f32x16& p1, float& l_reg, bf16x8& pa0, bf16x8& pa1, bf16x8& pa2, bf16x8& pa3) {
; #pragma unroll
;   for (int r = 0; r < 16; ++r) p1[r] = __builtin_amdgcn_exp2f(p1[r]);
;   asm volatile("s_nop 0" : "+v"(p1));
;   float s0 = fadd_s(p0[0], p0[1]), s1 = fadd_s(p0[2], p0[3]), s2 = fadd_s(p0[4], p0[5]), s3 = fadd_s(p0[6], p0[7]);
; #pragma unroll
;   for (int r = 8; r < 16; r += 4) { s0 = fadd_s(s0, p0[r]); s1 = fadd_s(s1, p0[r + 1]); s2 = fadd_s(s2, p0[r + 2]); s3 = fadd_s(s3, p0[r + 3]); }
; #pragma unroll
;   for (int r = 0; r < 16; r += 4) { s0 = fadd_s(s0, p1[r]); s1 = fadd_s(s1, p1[r + 1]); s2 = fadd_s(s2, p1[r + 2]); s3 = fadd_s(s3, p1[r + 3]); }
;   l_reg = fadd_s(l_reg, fadd_s(fadd_s(s0, s1), fadd_s(s2, s3)));
;     ...
;   PK4(p0, 0, pa0); PK4(p0, 8, pa1); PK4(p1, 0, pa2); PK4(p1, 8, pa3);
;     ...
; }
; __device__ __forceinline__ void qkt(f32x16& p0, f32x16& p1, const bf16_t* Ks, const bf16x8* qr, int r32, int hi) {
;   p0 = f32x16{}; p1 = f32x16{};
; #pragma unroll
;   for (int d0 = 0; d0 < 8; ++d0) { int cb = (d0 * 16 + hi * 8) * 2;
;     bf16x8 b0 = *reinterpret_cast<const bf16x8*>((const char*)Ks + KSWZ(r32, cb));
;     bf16x8 b1 = *reinterpret_cast<const bf16x8*>((const char*)Ks + KSWZ(32 + r32, cb));
;     p0 = __builtin_amdgcn_mfma_f32_32x32x16_bf16(b0, qr[d0], p0, 0, 0, 0);
;     p1 = __builtin_amdgcn_mfma_f32_32x32x16_bf16(b1, qr[d0], p1, 0, 0, 0); }
; }
; __device__ __forceinline__ int v_st(int k, int c) { const int kk = (k & ~0xC) | ((k & 4) << 1) | ((k & 8) >> 1); return ((kk >> 3) * 4 + (c >> 5)) * 512 + ((kk & 7) * 32 + (c & 31)) * 2; }
; __device__ __forceinline__ int v_rd_base(int lane) { return ((lane & 3) << 3) | (((lane >> 2) & 3) << 6) | (((lane >> 4) & 1) << 5) | (((lane >> 5) & 1) << 8); }
; template <int OFF> __device__ __forceinline__ s16x4 tr_read(int vb) {
;   s16x4 r; asm volatile("ds_read_b64_tr_b16 %0, %1 offset:%2" : "=&v"(r) : "v"(vb), "i"(OFF) : "memory"); return r;
; }
; template <int D0> __device__ __forceinline__ void pv_one(f32x16& od, int vb, bf16x8 pa0, bf16x8 pa1, bf16x8 pa2, bf16x8 pa3) {
;   const s16x4 l0 = tr_read<v_rd_off(D0, 0, 0)>(vb), h0 = tr_read<v_rd_off(D0, 0, 1)>(vb), l1 = tr_read<v_rd_off(D0, 1, 0)>(vb), h1 = tr_read<v_rd_off(D0, 1, 1)>(vb);
	v_mfma_f32_32x32x16_bf16 v[64:79], v[148:151], v[120:123], v[64:79]
	v_add_u32_e32 v148, s13, v162
	ds_read_b128 v[144:147], v148 offset:49152
	ds_read_b128 v[148:151], v148 offset:57344
	s_waitcnt lgkmcnt(1)
	v_mfma_f32_32x32x16_bf16 v[96:111], v[144:147], v[116:119], v[96:111]
	s_waitcnt lgkmcnt(0)
	v_mfma_f32_32x32x16_bf16 v[64:79], v[148:151], v[116:119], v[64:79]
	v_add_u32_e32 v148, s13, v159
	ds_read_b128 v[144:147], v148 offset:49152
	ds_read_b128 v[148:151], v148 offset:57344
	s_nop 0
	s_waitcnt lgkmcnt(1)
	v_mfma_f32_32x32x16_bf16 v[96:111], v[144:147], v[112:115], v[96:111]
	v_add_f32 v144, v183, v192
	v_add_f32 v145, v195, v204
	v_add_f32 v146, v205, v210
	v_add_f32 v147, v211, v212
	s_nop 0
	v_add_f32 v144, v144, v213
	v_add_f32 v145, v145, v214
	v_add_f32 v146, v146, v215
	v_add_f32 v147, v147, v216
	s_waitcnt lgkmcnt(0)
	v_mfma_f32_32x32x16_bf16 v[64:79], v[148:151], v[112:115], v[64:79]
	v_add_f32 v144, v144, v217
	v_add_f32 v145, v145, v218
	v_add_f32 v146, v146, v219
	v_add_f32 v147, v147, v220
	s_nop 0
	v_add_f32 v144, v144, v80
	v_add_f32 v145, v145, v81
	v_add_f32 v146, v146, v82
	v_add_f32 v147, v147, v83
	s_nop 0
	v_add_f32 v144, v144, v84
	v_add_f32 v145, v145, v85
	v_add_f32 v146, v146, v86
	v_add_f32 v147, v147, v87
	s_nop 0
	v_add_f32 v144, v144, v88
	v_add_f32 v145, v145, v89
	v_add_f32 v146, v146, v90
	v_add_f32 v147, v147, v91
	s_nop 0
	v_add_f32 v144, v144, v92
	v_add_f32 v145, v145, v93
	v_add_f32 v146, v146, v94
	v_add_f32 v147, v147, v95
	s_nop 0
	v_add_f32 v144, v144, v145
	v_add_f32 v145, v146, v147
	s_nop 0
	v_add_f32 v144, v144, v145
	s_nop 0
	v_add_f32 v179, v179, v144
	v_cvt_pk_bf16_f32 v144, v183, v192
	v_cvt_pk_bf16_f32 v145, v195, v204
	v_cvt_pk_bf16_f32 v146, v205, v210
	v_cvt_pk_bf16_f32 v147, v211, v212
	s_nop 0
	s_nop 1
	v_cvt_pk_bf16_f32 v148, v213, v214
	v_cvt_pk_bf16_f32 v149, v215, v216
	v_cvt_pk_bf16_f32 v150, v217, v218
	v_cvt_pk_bf16_f32 v151, v219, v220
	s_nop 0
	s_nop 1
	v_cvt_pk_bf16_f32 v80, v80, v81
	v_cvt_pk_bf16_f32 v81, v82, v83
	v_cvt_pk_bf16_f32 v82, v84, v85
	v_cvt_pk_bf16_f32 v83, v86, v87
	v_permlane32_swap_b32_e32 v144, v146
	s_nop 1
	v_cvt_pk_bf16_f32 v84, v88, v89
	v_cvt_pk_bf16_f32 v85, v90, v91
	v_cvt_pk_bf16_f32 v86, v92, v93
	v_cvt_pk_bf16_f32 v87, v94, v95
	v_permlane32_swap_b32_e32 v145, v147
	v_permlane32_swap_b32_e32 v148, v150
	v_permlane32_swap_b32_e32 v149, v151
	s_nop 1
	v_permlane32_swap_b32_e32 v80, v82
	v_permlane32_swap_b32_e32 v81, v83
	v_permlane32_swap_b32_e32 v84, v86
	v_permlane32_swap_b32_e32 v85, v87
	v_add_u32_e32 v183, s11, v157
	ds_read_b64_tr_b16 v[184:185], v183 offset:0
	ds_read_b64_tr_b16 v[186:187], v183 offset:0x800
	ds_read_b64_tr_b16 v[188:189], v183 offset:0x1000
	ds_read_b64_tr_b16 v[190:191], v183 offset:0x1800
	ds_read_b64_tr_b16 v[218:219], v183 offset:0x2000
	ds_read_b64_tr_b16 v[220:221], v183 offset:0x2800
	ds_read_b64_tr_b16 v[222:223], v183 offset:0x3000
	ds_read_b64_tr_b16 v[224:225], v183 offset:0x3800
	s_waitcnt lgkmcnt(0)
	s_nop 0
	v_mfma_f32_32x32x16_bf16 v[0:15], v[144:147], v[184:187], v[0:15]
	ds_read_b64_tr_b16 v[184:185], v183 offset:0x200
	ds_read_b64_tr_b16 v[186:187], v183 offset:0xa00
	v_mfma_f32_32x32x16_bf16 v[0:15], v[148:151], v[188:191], v[0:15]
	ds_read_b64_tr_b16 v[188:189], v183 offset:0x1200
	ds_read_b64_tr_b16 v[190:191], v183 offset:0x1a00
	v_mfma_f32_32x32x16_bf16 v[0:15], v[80:83], v[218:221], v[0:15]
	ds_read_b64_tr_b16 v[218:219], v183 offset:0x2200
	ds_read_b64_tr_b16 v[220:221], v183 offset:0x2a00
	v_mfma_f32_32x32x16_bf16 v[0:15], v[84:87], v[222:225], v[0:15]
	ds_read_b64_tr_b16 v[222:223], v183 offset:0x3200
	ds_read_b64_tr_b16 v[224:225], v183 offset:0x3a00
	s_waitcnt lgkmcnt(0)
	v_mfma_f32_32x32x16_bf16 v[16:31], v[144:147], v[184:187], v[16:31]
	ds_read_b64_tr_b16 v[184:185], v183 offset:0x400
	ds_read_b64_tr_b16 v[186:187], v183 offset:0xc00
	v_mfma_f32_32x32x16_bf16 v[16:31], v[148:151], v[188:191], v[16:31]
	ds_read_b64_tr_b16 v[188:189], v183 offset:0x1400
	ds_read_b64_tr_b16 v[190:191], v183 offset:0x1c00
	v_mfma_f32_32x32x16_bf16 v[16:31], v[80:83], v[218:221], v[16:31]
	ds_read_b64_tr_b16 v[218:219], v183 offset:0x2400
	ds_read_b64_tr_b16 v[220:221], v183 offset:0x2c00
	v_mfma_f32_32x32x16_bf16 v[16:31], v[84:87], v[222:225], v[16:31]
	ds_read_b64_tr_b16 v[222:223], v183 offset:0x3400
	ds_read_b64_tr_b16 v[224:225], v183 offset:0x3c00
	s_waitcnt lgkmcnt(0)
	v_mfma_f32_32x32x16_bf16 v[32:47], v[144:147], v[184:187], v[32:47]
	ds_read_b64_tr_b16 v[184:185], v183 offset:0x600
	ds_read_b64_tr_b16 v[186:187], v183 offset:0xe00
	v_mfma_f32_32x32x16_bf16 v[32:47], v[148:151], v[188:191], v[32:47]
	ds_read_b64_tr_b16 v[188:189], v183 offset:0x1600
	ds_read_b64_tr_b16 v[190:191], v183 offset:0x1e00
	v_mfma_f32_32x32x16_bf16 v[32:47], v[80:83], v[218:221], v[32:47]
	ds_read_b64_tr_b16 v[218:219], v183 offset:0x2600
	ds_read_b64_tr_b16 v[220:221], v183 offset:0x2e00
	v_mfma_f32_32x32x16_bf16 v[32:47], v[84:87], v[222:225], v[32:47]
	ds_read_b64_tr_b16 v[222:223], v183 offset:0x3600
	ds_read_b64_tr_b16 v[224:225], v183 offset:0x3e00
	s_waitcnt lgkmcnt(0)
	v_mfma_f32_32x32x16_bf16 v[48:63], v[144:147], v[184:187], v[48:63]
	s_add_i32 s13, s9, 0
	v_exp_f32_e32 v144, v96
	v_exp_f32_e32 v145, v97
	v_exp_f32_e32 v147, v98
	v_exp_f32_e32 v146, v100
	v_exp_f32_e32 v187, v101
	v_exp_f32_e32 v183, v108
	v_mfma_f32_32x32x16_bf16 v[48:63], v[148:151], v[188:191], v[48:63]
	v_exp_f32_e32 v188, v99
	v_exp_f32_e32 v189, v102
	v_exp_f32_e32 v190, v103
	v_exp_f32_e32 v148, v104
	v_exp_f32_e32 v149, v105
	v_exp_f32_e32 v150, v106
	v_exp_f32_e32 v151, v107
	v_mfma_f32_32x32x16_bf16 v[48:63], v[80:83], v[218:221], v[48:63]
	v_exp_f32_e32 v184, v109
	v_exp_f32_e32 v185, v110
	v_exp_f32_e32 v186, v111
	v_add_u32_e32 v80, s13, v170
	s_waitcnt vmcnt(0)
	s_waitcnt vmcnt(3)
	ds_write_b128 v80, v[226:229]
	v_add_u32_e32 v80, s13, v171
	v_mfma_f32_32x32x16_bf16 v[48:63], v[84:87], v[222:225], v[48:63]
	s_waitcnt vmcnt(1)
	ds_write_b128 v80, v[234:237]
	v_add_u32_e32 v80, s13, v165
	s_add_i32 s10, s10, 2
	s_mov_b64 s[42:43], 0x2c0000
	ds_write_b128 v80, v[230:233] offset:49152
	v_add_u32_e32 v80, s13, v168
	v_lshl_add_u64 v[152:153], v[152:153], 0, s[42:43]
	s_cmp_lt_u32 s10, 27
	s_mov_b32 s13, s11
	s_mov_b32 s11, s9
	s_mov_b32 s9, s12
	s_waitcnt vmcnt(0)
	ds_write_b128 v80, v[238:241] offset:49152
	s_waitcnt lgkmcnt(0)
	s_barrier
; __device__ __forceinline__ float fadd_s(float a, float b) { float r; asm("v_add_f32 %0, %1, %2" : "=v"(r) : "v"(a), "v"(b)); return r; }
; __device__ __forceinline__ void finishSM(f32x16& p0, f32x16& p1, float& l_reg, bf16x8& pa0, bf16x8& pa1, bf16x8& pa2, bf16x8& pa3) {
; #pragma unroll
;   for (int r = 0; r < 16; ++r) p1[r] = __builtin_amdgcn_exp2f(p1[r]);
;   asm volatile("s_nop 0" : "+v"(p1));
;   float s0 = fadd_s(p0[0], p0[1]), s1 = fadd_s(p0[2], p0[3]), s2 = fadd_s(p0[4], p0[5]), s3 = fadd_s(p0[6], p0[7]);
; #pragma unroll
;   for (int r = 8; r < 16; r += 4) { s0 = fadd_s(s0, p0[r]); s1 = fadd_s(s1, p0[r + 1]); s2 = fadd_s(s2, p0[r + 2]); s3 = fadd_s(s3, p0[r + 3]); }
; #pragma unroll
;   for (int r = 0; r < 16; r += 4) { s0 = fadd_s(s0, p1[r]); s1 = fadd_s(s1, p1[r + 1]); s2 = fadd_s(s2, p1[r + 2]); s3 = fadd_s(s3, p1[r + 3]); }
;   l_reg = fadd_s(l_reg, fadd_s(fadd_s(s0, s1), fadd_s(s2, s3)));
;     ...
;   PK4(p0, 0, pa0); PK4(p0, 8, pa1); PK4(p1, 0, pa2); PK4(p1, 8, pa3);
;     ...
; }
; __device__ __forceinline__ void qkt(f32x16& p0, f32x16& p1, const bf16_t* Ks, const bf16x8* qr, int r32, int hi) {
;   p0 = f32x16{}; p1 = f32x16{};
; #pragma unroll
;   for (int d0 = 0; d0 < 8; ++d0) { int cb = (d0 * 16 + hi * 8) * 2;
;     bf16x8 b0 = *reinterpret_cast<const bf16x8*>((const char*)Ks + KSWZ(r32, cb));
;     bf16x8 b1 = *reinterpret_cast<const bf16x8*>((const char*)Ks + KSWZ(32 + r32, cb));
;     p0 = __builtin_amdgcn_mfma_f32_32x32x16_bf16(b0, qr[d0], p0, 0, 0, 0);
;     p1 = __builtin_amdgcn_mfma_f32_32x32x16_bf16(b1, qr[d0], p1, 0, 0, 0); }
; }
; __device__ __forceinline__ void attn_dense_body(const bf16_t* Qb, const bf16_t* __restrict__ Kh, const bf16_t* __restrict__ Vh, bf16_t* Ob, int seq, char* lds, const int wid,
;                                                 const float* __restrict__ qg, const float* __restrict__ rope, int t0) {
;     ...
;   STEP(pA0, pA1, pB0, pB1, j, true, false);
	s_cbranch_scc1 .LBB0_495
	v_or_b32_e32 v152, 0x2000, v176
	v_add_u32_e32 v80, s8, v177
	v_add3_u32 v84, v175, v152, s8
	ds_read_b128 v[80:83], v80
	ds_read_b128 v[84:87], v84
	v_add3_u32 v153, v174, v152, s8
	v_exp_f32_e32 v64, v64
	v_exp_f32_e32 v65, v65
	v_exp_f32_e32 v66, v66
	v_exp_f32_e32 v67, v67
	v_exp_f32_e32 v68, v68
	s_waitcnt lgkmcnt(1)
	v_mfma_f32_32x32x16_bf16 v[96:111], v[80:83], v[140:143], 0
	ds_read_b128 v[174:177], v153
	v_exp_f32_e32 v69, v69
	v_exp_f32_e32 v70, v70
	v_exp_f32_e32 v71, v71
	v_exp_f32_e32 v72, v72
	v_exp_f32_e32 v73, v73
	v_exp_f32_e32 v74, v74
	s_waitcnt lgkmcnt(1)
	v_mfma_f32_32x32x16_bf16 v[80:95], v[84:87], v[140:143], 0
	v_add_u32_e32 v140, s8, v178
	ds_read_b128 v[140:143], v140
	v_exp_f32_e32 v75, v75
	v_exp_f32_e32 v76, v76
	v_exp_f32_e32 v77, v77
	v_exp_f32_e32 v78, v78
	v_exp_f32_e32 v79, v79
	s_waitcnt lgkmcnt(0)
	v_mfma_f32_32x32x16_bf16 v[96:111], v[140:143], v[136:139], v[96:111]
	v_add3_u32 v140, v172, v152, s8
	ds_read_b128 v[140:143], v140
	v_mfma_f32_32x32x16_bf16 v[80:95], v[174:177], v[136:139], v[80:95]
	v_add_u32_e32 v136, s8, v173
	ds_read_b128 v[136:139], v136
	s_waitcnt lgkmcnt(0)
	v_mfma_f32_32x32x16_bf16 v[96:111], v[136:139], v[132:135], v[96:111]
	v_add3_u32 v136, v166, v152, s8
	ds_read_b128 v[136:139], v136
	v_mfma_f32_32x32x16_bf16 v[80:95], v[140:143], v[132:135], v[80:95]
	v_add_u32_e32 v132, s8, v169
	ds_read_b128 v[132:135], v132
	s_waitcnt lgkmcnt(0)
	v_mfma_f32_32x32x16_bf16 v[96:111], v[132:135], v[128:131], v[96:111]
	v_add3_u32 v132, v164, v152, s8
	ds_read_b128 v[132:135], v132
	v_mfma_f32_32x32x16_bf16 v[80:95], v[136:139], v[128:131], v[80:95]
	v_add_u32_e32 v128, s8, v167
	ds_read_b128 v[128:131], v128
	s_waitcnt lgkmcnt(0)
	v_mfma_f32_32x32x16_bf16 v[96:111], v[128:131], v[124:127], v[96:111]
	v_add3_u32 v128, v161, v152, s8
	ds_read_b128 v[128:131], v128
	v_mfma_f32_32x32x16_bf16 v[80:95], v[132:135], v[124:127], v[80:95]
	v_add_u32_e32 v124, s8, v163
	ds_read_b128 v[124:127], v124
	s_waitcnt lgkmcnt(0)
	v_mfma_f32_32x32x16_bf16 v[96:111], v[124:127], v[120:123], v[96:111]
	v_add3_u32 v124, v160, v152, s8
	ds_read_b128 v[124:127], v124
	v_mfma_f32_32x32x16_bf16 v[80:95], v[128:131], v[120:123], v[80:95]
	v_add_u32_e32 v120, s8, v162
	ds_read_b128 v[120:123], v120
	s_waitcnt lgkmcnt(0)
	v_mfma_f32_32x32x16_bf16 v[96:111], v[120:123], v[116:119], v[96:111]
	v_add3_u32 v120, v158, v152, s8
	ds_read_b128 v[120:123], v120
	v_mfma_f32_32x32x16_bf16 v[80:95], v[124:127], v[116:119], v[80:95]
	v_add_u32_e32 v116, s8, v159
	ds_read_b128 v[116:119], v116
	s_nop 0
	s_waitcnt lgkmcnt(0)
	v_mfma_f32_32x32x16_bf16 v[96:111], v[116:119], v[112:115], v[96:111]
	v_mfma_f32_32x32x16_bf16 v[80:95], v[120:123], v[112:115], v[80:95]
	v_add_f32 v112, v144, v145
	v_add_f32 v113, v147, v188
	v_add_f32 v114, v146, v187
	v_add_f32 v115, v189, v190
	s_nop 0
	v_add_f32 v112, v112, v148
	v_add_f32 v113, v113, v149
	v_add_f32 v114, v114, v150
	v_add_f32 v115, v115, v151
	s_nop 0
	v_add_f32 v112, v112, v183
	v_add_f32 v113, v113, v184
	v_add_f32 v114, v114, v185
	v_add_f32 v115, v115, v186
	s_nop 0
	v_add_f32 v112, v112, v64
	v_add_f32 v113, v113, v65
	v_add_f32 v114, v114, v66
	v_add_f32 v115, v115, v67
	s_nop 0
	v_add_f32 v112, v112, v68
	v_add_f32 v113, v113, v69
	v_add_f32 v114, v114, v70
	v_add_f32 v115, v115, v71
	s_nop 0
	v_add_f32 v112, v112, v72
	v_add_f32 v113, v113, v73
	v_add_f32 v114, v114, v74
	v_add_f32 v115, v115, v75
	s_nop 0
	v_add_f32 v112, v112, v76
	v_add_f32 v113, v113, v77
	v_add_f32 v114, v114, v78
	v_add_f32 v115, v115, v79
	s_nop 0
	v_add_f32 v112, v112, v113
	v_add_f32 v113, v114, v115
	s_nop 0
	v_add_f32 v112, v112, v113
	s_nop 0
	v_add_f32 v128, v179, v112
	v_cvt_pk_bf16_f32 v112, v144, v145
	v_cvt_pk_bf16_f32 v113, v147, v188
	v_cvt_pk_bf16_f32 v114, v146, v187
	v_cvt_pk_bf16_f32 v115, v189, v190
	s_nop 0
	s_nop 1
	v_cvt_pk_bf16_f32 v116, v148, v149
	v_cvt_pk_bf16_f32 v117, v150, v151
	v_cvt_pk_bf16_f32 v118, v183, v184
	v_cvt_pk_bf16_f32 v119, v185, v186
	s_nop 0
	s_nop 1
	v_cvt_pk_bf16_f32 v64, v64, v65
	v_cvt_pk_bf16_f32 v65, v66, v67
	v_cvt_pk_bf16_f32 v66, v68, v69
	v_cvt_pk_bf16_f32 v67, v70, v71
	v_permlane32_swap_b32_e32 v112, v114
	s_nop 1
	v_cvt_pk_bf16_f32 v68, v72, v73
	v_cvt_pk_bf16_f32 v69, v74, v75
	v_cvt_pk_bf16_f32 v70, v76, v77
	v_cvt_pk_bf16_f32 v71, v78, v79
	v_permlane32_swap_b32_e32 v113, v115
	v_permlane32_swap_b32_e32 v64, v66
	s_nop 1
	v_permlane32_swap_b32_e32 v116, v118
	v_permlane32_swap_b32_e32 v117, v119
	v_permlane32_swap_b32_e32 v65, v67
	v_permlane32_swap_b32_e32 v68, v70
	v_permlane32_swap_b32_e32 v69, v71
	ds_read_b64_tr_b16 v[72:73], v157 offset:0
	ds_read_b64_tr_b16 v[74:75], v157 offset:0x800
	ds_read_b64_tr_b16 v[76:77], v157 offset:0x1000
	ds_read_b64_tr_b16 v[78:79], v157 offset:0x1800
	ds_read_b64_tr_b16 v[120:121], v157 offset:0x2000
	ds_read_b64_tr_b16 v[122:123], v157 offset:0x2800
	ds_read_b64_tr_b16 v[124:125], v157 offset:0x3000
	ds_read_b64_tr_b16 v[126:127], v157 offset:0x3800
	s_waitcnt lgkmcnt(0)
	s_nop 0
	v_mfma_f32_32x32x16_bf16 v[0:15], v[112:115], v[72:75], v[0:15]
	ds_read_b64_tr_b16 v[72:73], v157 offset:0x200
	ds_read_b64_tr_b16 v[74:75], v157 offset:0xa00
	v_mfma_f32_32x32x16_bf16 v[0:15], v[116:119], v[76:79], v[0:15]
	ds_read_b64_tr_b16 v[76:77], v157 offset:0x1200
	ds_read_b64_tr_b16 v[78:79], v157 offset:0x1a00
	v_mfma_f32_32x32x16_bf16 v[0:15], v[64:67], v[120:123], v[0:15]
	ds_read_b64_tr_b16 v[120:121], v157 offset:0x2200
	ds_read_b64_tr_b16 v[122:123], v157 offset:0x2a00
	v_mfma_f32_32x32x16_bf16 v[0:15], v[68:71], v[124:127], v[0:15]
	ds_read_b64_tr_b16 v[124:125], v157 offset:0x3200
	ds_read_b64_tr_b16 v[126:127], v157 offset:0x3a00
	s_waitcnt lgkmcnt(0)
; #define SBAR() __builtin_amdgcn_sched_barrier(0)
; __device__ __forceinline__ void expHalf(f32x16& p0) {
; #pragma unroll
;   for (int r = 0; r < 16; ++r) p0[r] = __builtin_amdgcn_exp2f(p0[r]);
; }
; template <int D0> __device__ __forceinline__ void pv_one(f32x16& od, int vb, bf16x8 pa0, bf16x8 pa1, bf16x8 pa2, bf16x8 pa3) {
;   const s16x4 l0 = tr_read<v_rd_off(D0, 0, 0)>(vb), h0 = tr_read<v_rd_off(D0, 0, 1)>(vb), l1 = tr_read<v_rd_off(D0, 1, 0)>(vb), h1 = tr_read<v_rd_off(D0, 1, 1)>(vb);
;   const s16x4 l2 = tr_read<v_rd_off(D0, 2, 0)>(vb), h2 = tr_read<v_rd_off(D0, 2, 1)>(vb), l3 = tr_read<v_rd_off(D0, 3, 0)>(vb), h3 = tr_read<v_rd_off(D0, 3, 1)>(vb);
;   asm volatile("s_waitcnt lgkmcnt(0)" ::: "memory"); SBAR();
;     ...
;   od = __builtin_amdgcn_mfma_f32_32x32x16_bf16(pa0, PK(l0, h0), od, 0, 0, 0);
;   od = __builtin_amdgcn_mfma_f32_32x32x16_bf16(pa1, PK(l1, h1), od, 0, 0, 0);
;   od = __builtin_amdgcn_mfma_f32_32x32x16_bf16(pa2, PK(l2, h2), od, 0, 0, 0);
;   od = __builtin_amdgcn_mfma_f32_32x32x16_bf16(pa3, PK(l3, h3), od, 0, 0, 0);
;     ...
; }
; __device__ __forceinline__ void pv_d0(f32x16* o, int vb, bf16x8 pa0, bf16x8 pa1, bf16x8 pa2, bf16x8 pa3) {
;   pv_one<0>(o[0], vb, pa0, pa1, pa2, pa3); pv_one<1>(o[1], vb, pa0, pa1, pa2, pa3); pv_one<2>(o[2], vb, pa0, pa1, pa2, pa3); pv_one<3>(o[3], vb, pa0, pa1, pa2, pa3);
	v_mfma_f32_32x32x16_bf16 v[16:31], v[112:115], v[72:75], v[16:31]
	ds_read_b64_tr_b16 v[72:73], v157 offset:0x400
	ds_read_b64_tr_b16 v[74:75], v157 offset:0xc00
	v_mfma_f32_32x32x16_bf16 v[16:31], v[116:119], v[76:79], v[16:31]
	ds_read_b64_tr_b16 v[76:77], v157 offset:0x1400
	ds_read_b64_tr_b16 v[78:79], v157 offset:0x1c00
	v_mfma_f32_32x32x16_bf16 v[16:31], v[64:67], v[120:123], v[16:31]
	ds_read_b64_tr_b16 v[120:121], v157 offset:0x2400
	ds_read_b64_tr_b16 v[122:123], v157 offset:0x2c00
	v_mfma_f32_32x32x16_bf16 v[16:31], v[68:71], v[124:127], v[16:31]
	ds_read_b64_tr_b16 v[124:125], v157 offset:0x3400
	ds_read_b64_tr_b16 v[126:127], v157 offset:0x3c00
	s_waitcnt lgkmcnt(0)
	v_mfma_f32_32x32x16_bf16 v[32:47], v[112:115], v[72:75], v[32:47]
	ds_read_b64_tr_b16 v[72:73], v157 offset:0x600
	ds_read_b64_tr_b16 v[74:75], v157 offset:0xe00
	v_mfma_f32_32x32x16_bf16 v[32:47], v[116:119], v[76:79], v[32:47]
	ds_read_b64_tr_b16 v[76:77], v157 offset:0x1600
	ds_read_b64_tr_b16 v[78:79], v157 offset:0x1e00
	v_mfma_f32_32x32x16_bf16 v[32:47], v[64:67], v[120:123], v[32:47]
	ds_read_b64_tr_b16 v[120:121], v157 offset:0x2600
	ds_read_b64_tr_b16 v[122:123], v157 offset:0x2e00
	v_mfma_f32_32x32x16_bf16 v[32:47], v[68:71], v[124:127], v[32:47]
	ds_read_b64_tr_b16 v[124:125], v157 offset:0x3600
	ds_read_b64_tr_b16 v[126:127], v157 offset:0x3e00
	s_waitcnt lgkmcnt(0)
	v_mfma_f32_32x32x16_bf16 v[48:63], v[112:115], v[72:75], v[48:63]
	v_exp_f32_e32 v96, v96
	v_exp_f32_e32 v97, v97
	v_exp_f32_e32 v98, v98
	v_exp_f32_e32 v99, v99
	v_exp_f32_e32 v100, v100
	v_exp_f32_e32 v101, v101
	v_exp_f32_e32 v102, v102
	v_mfma_f32_32x32x16_bf16 v[48:63], v[116:119], v[76:79], v[48:63]
	v_exp_f32_e32 v103, v103
	v_exp_f32_e32 v104, v104
	v_exp_f32_e32 v105, v105
	v_exp_f32_e32 v106, v106
	v_exp_f32_e32 v107, v107
	v_exp_f32_e32 v108, v108
	v_exp_f32_e32 v109, v109
	v_mfma_f32_32x32x16_bf16 v[48:63], v[64:67], v[120:123], v[48:63]
	v_exp_f32_e32 v110, v110
	v_exp_f32_e32 v111, v111
	s_barrier
; __device__ __forceinline__ void finishSM(f32x16& p0, f32x16& p1, float& l_reg, bf16x8& pa0, bf16x8& pa1, bf16x8& pa2, bf16x8& pa3) {
; #pragma unroll
;   for (int r = 0; r < 16; ++r) p1[r] = __builtin_amdgcn_exp2f(p1[r]);
;   asm volatile("s_nop 0" : "+v"(p1));
;   float s0 = fadd_s(p0[0], p0[1]), s1 = fadd_s(p0[2], p0[3]), s2 = fadd_s(p0[4], p0[5]), s3 = fadd_s(p0[6], p0[7]);
; #pragma unroll
;   for (int r = 8; r < 16; r += 4) { s0 = fadd_s(s0, p0[r]); s1 = fadd_s(s1, p0[r + 1]); s2 = fadd_s(s2, p0[r + 2]); s3 = fadd_s(s3, p0[r + 3]); }
; #pragma unroll
;   for (int r = 0; r < 16; r += 4) { s0 = fadd_s(s0, p1[r]); s1 = fadd_s(s1, p1[r + 1]); s2 = fadd_s(s2, p1[r + 2]); s3 = fadd_s(s3, p1[r + 3]); }
;   l_reg = fadd_s(l_reg, fadd_s(fadd_s(s0, s1), fadd_s(s2, s3)));
;     ...
;   PK4(p0, 0, pa0); PK4(p0, 8, pa1); PK4(p1, 0, pa2); PK4(p1, 8, pa3);
;     ...
; }
; __device__ __forceinline__ void qkt(f32x16& p0, f32x16& p1, const bf16_t* Ks, const bf16x8* qr, int r32, int hi) {
;   p0 = f32x16{}; p1 = f32x16{};
; #pragma unroll
;   for (int d0 = 0; d0 < 8; ++d0) { int cb = (d0 * 16 + hi * 8) * 2;
;     bf16x8 b0 = *reinterpret_cast<const bf16x8*>((const char*)Ks + KSWZ(r32, cb));
;     bf16x8 b1 = *reinterpret_cast<const bf16x8*>((const char*)Ks + KSWZ(32 + r32, cb));
;     p0 = __builtin_amdgcn_mfma_f32_32x32x16_bf16(b0, qr[d0], p0, 0, 0, 0);
;     p1 = __builtin_amdgcn_mfma_f32_32x32x16_bf16(b1, qr[d0], p1, 0, 0, 0); }
; }
; __device__ __forceinline__ int v_st(int k, int c) { const int kk = (k & ~0xC) | ((k & 4) << 1) | ((k & 8) >> 1); return ((kk >> 3) * 4 + (c >> 5)) * 512 + ((kk & 7) * 32 + (c & 31)) * 2; }
; __device__ __forceinline__ int v_rd_base(int lane) { return ((lane & 3) << 3) | (((lane >> 2) & 3) << 6) | (((lane >> 4) & 1) << 5) | (((lane >> 5) & 1) << 8); }
; template <int OFF> __device__ __forceinline__ s16x4 tr_read(int vb) {
;   s16x4 r; asm volatile("ds_read_b64_tr_b16 %0, %1 offset:%2" : "=&v"(r) : "v"(vb), "i"(OFF) : "memory"); return r;
; }
; template <int D0> __device__ __forceinline__ void pv_one(f32x16& od, int vb, bf16x8 pa0, bf16x8 pa1, bf16x8 pa2, bf16x8 pa3) {
;   const s16x4 l0 = tr_read<v_rd_off(D0, 0, 0)>(vb), h0 = tr_read<v_rd_off(D0, 0, 1)>(vb), l1 = tr_read<v_rd_off(D0, 1, 0)>(vb), h1 = tr_read<v_rd_off(D0, 1, 1)>(vb);
	v_mfma_f32_32x32x16_bf16 v[48:63], v[68:71], v[124:127], v[48:63]
	v_exp_f32_e32 v64, v80
	v_add_f32 v80, v96, v97
	v_exp_f32_e32 v65, v81
	v_add_f32 v81, v98, v99
	v_add_f32 v80, v80, v104
	v_exp_f32_e32 v66, v82
	v_exp_f32_e32 v67, v83
	v_exp_f32_e32 v68, v84
	v_exp_f32_e32 v69, v85
	v_exp_f32_e32 v70, v86
	v_exp_f32_e32 v71, v87
	v_exp_f32_e32 v72, v88
	v_exp_f32_e32 v73, v89
	v_exp_f32_e32 v74, v90
	v_exp_f32_e32 v75, v91
	v_exp_f32_e32 v76, v92
	v_exp_f32_e32 v77, v93
	v_exp_f32_e32 v78, v94
	v_exp_f32_e32 v79, v95
	v_add_f32 v82, v100, v101
	v_add_f32 v83, v102, v103
	v_add_f32 v81, v81, v105
	v_add_f32 v80, v80, v108
	s_nop 0
	s_nop 0
	v_add_f32 v82, v82, v106
	v_add_f32 v83, v83, v107
	v_add_f32 v81, v81, v109
	v_add_f32 v80, v80, v64
	s_nop 0
	v_add_f32 v82, v82, v110
	v_add_f32 v83, v83, v111
	v_add_f32 v81, v81, v65
	v_add_f32 v80, v80, v68
	s_nop 0
	v_add_f32 v82, v82, v66
	v_add_f32 v83, v83, v67
	v_add_f32 v81, v81, v69
	v_add_f32 v80, v80, v72
	s_nop 0
	v_add_f32 v82, v82, v70
	v_add_f32 v83, v83, v71
	v_add_f32 v81, v81, v73
	v_add_f32 v80, v80, v76
	s_nop 0
	v_add_f32 v82, v82, v74
	v_add_f32 v83, v83, v75
	v_add_f32 v81, v81, v77
	s_nop 0
	v_add_f32 v80, v80, v81
	v_add_f32 v82, v82, v78
	v_add_f32 v83, v83, v79
	s_nop 0
	v_add_f32 v81, v82, v83
	s_nop 0
	v_add_f32 v80, v80, v81
	s_nop 0
	v_add_f32 v88, v128, v80
	v_cvt_pk_bf16_f32 v80, v96, v97
	v_cvt_pk_bf16_f32 v81, v98, v99
	v_cvt_pk_bf16_f32 v82, v100, v101
	v_cvt_pk_bf16_f32 v83, v102, v103
	s_nop 0
	s_nop 1
	v_cvt_pk_bf16_f32 v84, v104, v105
	v_cvt_pk_bf16_f32 v85, v106, v107
	v_cvt_pk_bf16_f32 v86, v108, v109
	v_cvt_pk_bf16_f32 v87, v110, v111
	s_nop 0
	s_nop 1
	v_cvt_pk_bf16_f32 v64, v64, v65
	v_cvt_pk_bf16_f32 v65, v66, v67
	v_cvt_pk_bf16_f32 v66, v68, v69
	v_cvt_pk_bf16_f32 v67, v70, v71
	v_permlane32_swap_b32_e32 v80, v82
	s_nop 1
	v_cvt_pk_bf16_f32 v68, v72, v73
	v_cvt_pk_bf16_f32 v69, v74, v75
	v_cvt_pk_bf16_f32 v70, v76, v77
	v_cvt_pk_bf16_f32 v71, v78, v79
	v_permlane32_swap_b32_e32 v81, v83
	v_permlane32_swap_b32_e32 v64, v66
	s_nop 1
	v_permlane32_swap_b32_e32 v84, v86
	v_permlane32_swap_b32_e32 v85, v87
	v_permlane32_swap_b32_e32 v65, v67
	v_permlane32_swap_b32_e32 v68, v70
	v_permlane32_swap_b32_e32 v69, v71
	s_cmp_lg_u32 0, -1
	s_cselect_b32 s8, 0, 0
	s_addk_i32 s8, 0x4000
	v_add_u32_e32 v89, s8, v156
	ds_read_b64_tr_b16 v[72:73], v89 offset:0
	ds_read_b64_tr_b16 v[74:75], v89 offset:0x800
	ds_read_b64_tr_b16 v[76:77], v89 offset:0x1000
	ds_read_b64_tr_b16 v[78:79], v89 offset:0x1800
	ds_read_b64_tr_b16 v[90:91], v89 offset:0x2000
	ds_read_b64_tr_b16 v[92:93], v89 offset:0x2800
	ds_read_b64_tr_b16 v[94:95], v89 offset:0x3000
	ds_read_b64_tr_b16 v[96:97], v89 offset:0x3800
	s_waitcnt lgkmcnt(0)
	s_nop 0
	v_mfma_f32_32x32x16_bf16 v[0:15], v[80:83], v[72:75], v[0:15]
	ds_read_b64_tr_b16 v[72:73], v89 offset:0x200
	ds_read_b64_tr_b16 v[74:75], v89 offset:0xa00
	v_mfma_f32_32x32x16_bf16 v[0:15], v[84:87], v[76:79], v[0:15]
	ds_read_b64_tr_b16 v[76:77], v89 offset:0x1200
	ds_read_b64_tr_b16 v[78:79], v89 offset:0x1a00
	v_mfma_f32_32x32x16_bf16 v[0:15], v[64:67], v[90:93], v[0:15]
	ds_read_b64_tr_b16 v[90:91], v89 offset:0x2200
	ds_read_b64_tr_b16 v[92:93], v89 offset:0x2a00
	v_mfma_f32_32x32x16_bf16 v[0:15], v[68:71], v[94:97], v[0:15]
	ds_read_b64_tr_b16 v[94:95], v89 offset:0x3200
	ds_read_b64_tr_b16 v[96:97], v89 offset:0x3a00
	s_waitcnt lgkmcnt(0)
	v_mfma_f32_32x32x16_bf16 v[16:31], v[80:83], v[72:75], v[16:31]
	ds_read_b64_tr_b16 v[72:73], v89 offset:0x400
	ds_read_b64_tr_b16 v[74:75], v89 offset:0xc00
	v_mfma_f32_32x32x16_bf16 v[16:31], v[84:87], v[76:79], v[16:31]
	ds_read_b64_tr_b16 v[76:77], v89 offset:0x1400
	ds_read_b64_tr_b16 v[78:79], v89 offset:0x1c00
	v_mfma_f32_32x32x16_bf16 v[16:31], v[64:67], v[90:93], v[16:31]
	ds_read_b64_tr_b16 v[90:91], v89 offset:0x2400
	ds_read_b64_tr_b16 v[92:93], v89 offset:0x2c00
	v_mfma_f32_32x32x16_bf16 v[16:31], v[68:71], v[94:97], v[16:31]
	ds_read_b64_tr_b16 v[94:95], v89 offset:0x3400
	ds_read_b64_tr_b16 v[96:97], v89 offset:0x3c00
	s_waitcnt lgkmcnt(0)
	v_mfma_f32_32x32x16_bf16 v[32:47], v[80:83], v[72:75], v[32:47]
	ds_read_b64_tr_b16 v[72:73], v89 offset:0x600
	ds_read_b64_tr_b16 v[74:75], v89 offset:0xe00
	v_mfma_f32_32x32x16_bf16 v[32:47], v[84:87], v[76:79], v[32:47]
	ds_read_b64_tr_b16 v[76:77], v89 offset:0x1600
	ds_read_b64_tr_b16 v[78:79], v89 offset:0x1e00
	v_mfma_f32_32x32x16_bf16 v[32:47], v[64:67], v[90:93], v[32:47]
	ds_read_b64_tr_b16 v[90:91], v89 offset:0x2600
	ds_read_b64_tr_b16 v[92:93], v89 offset:0x2e00
	v_mfma_f32_32x32x16_bf16 v[32:47], v[68:71], v[94:97], v[32:47]
	ds_read_b64_tr_b16 v[94:95], v89 offset:0x3600
	ds_read_b64_tr_b16 v[96:97], v89 offset:0x3e00
	s_waitcnt lgkmcnt(0)
	v_mfma_f32_32x32x16_bf16 v[48:63], v[80:83], v[72:75], v[48:63]
	s_barrier
	v_mfma_f32_32x32x16_bf16 v[48:63], v[84:87], v[76:79], v[48:63]
	v_mfma_f32_32x32x16_bf16 v[48:63], v[64:67], v[90:93], v[48:63]
	v_mfma_f32_32x32x16_bf16 v[48:63], v[68:71], v[94:97], v[48:63]
	s_setprio 0
	v_mov_b32_e32 v64, v88
	s_nop 1
	v_permlane32_swap_b32_e32 v88, v64
	v_cmp_gt_u32_e32 vcc, 32, v180
	s_and_saveexec_b64 s[8:9], vcc
	s_cbranch_execz .LBB0_491
	v_readlane_b32 s4, v254, 32
	v_add_f32_e32 v64, v88, v64
	s_nop 0
	v_lshl_add_u32 v65, v182, 2, s4
	ds_write_b32 v65, v64
	s_branch .LBB0_491
